# static priority: waves 4-7 run the attention tile loop at s_setprio 1 (reset at loop exit), no per-segment toggles; otherwise as v68
# speedup vs baseline: 1.0169x; 1.0169x over previous
.LBB0_288:
	s_and_b64 s[16:17], s[18:19], exec
	v_mov_b32_e32 v128, v233
	s_cselect_b32 s16, s42, s41
	s_lshl_b32 s48, s16, 8
	v_readfirstlane_b32 s50, v128
	s_ashr_i32 s17, s50, 6
	s_or_b32 s49, s48, s43
	s_lshl_b32 s48, s17, 5
	s_add_i32 s49, s49, s48
	v_bfe_u32 v49, v128, 4, 2
	v_or_b32_e32 v0, s49, v49
	v_ashrrev_i32_e32 v1, 31, v0
	v_lshlrev_b64 v[0:1], 11, v[0:1]
	v_and_b32_e32 v48, 15, v128
	v_lshl_add_u64 v[0:1], s[12:13], 0, v[0:1]
	v_lshlrev_b32_e32 v168, 4, v48
	v_lshl_add_u64 v[24:25], v[0:1], 0, v[168:169]
	v_add_co_u32_e32 v4, vcc, s65, v24
	v_ashrrev_i32_e32 v50, 4, v128
	s_nop 0
	v_addc_co_u32_e32 v5, vcc, 0, v25, vcc
	v_add_co_u32_e32 v8, vcc, s63, v24
	v_lshlrev_b32_e32 v32, 3, v48
	s_nop 0
	v_addc_co_u32_e32 v9, vcc, 0, v25, vcc
	v_add_co_u32_e32 v12, vcc, s64, v24
	v_add_lshl_u32 v33, v50, s43, 10
	s_nop 0
	v_addc_co_u32_e32 v13, vcc, 0, v25, vcc
	v_add_co_u32_e32 v16, vcc, s33, v24
	v_or3_b32 v32, v33, v32, s44
	s_nop 0
	v_addc_co_u32_e32 v17, vcc, 0, v25, vcc
	v_add_co_u32_e32 v20, vcc, s69, v24
	v_lshlrev_b32_e32 v51, 4, v128
	s_nop 0
	v_addc_co_u32_e32 v21, vcc, 0, v25, vcc
	v_add_co_u32_e32 v26, vcc, s70, v24
	v_ashrrev_i32_e32 v53, 3, v128
	s_nop 0
	v_addc_co_u32_e32 v27, vcc, 0, v25, vcc
	s_mov_b32 s48, 0xe000
	v_lshlrev_b32_e32 v242, 1, v32
	v_and_b32_e32 v52, 0x70, v51
	v_add_u32_e32 v32, s45, v53
	v_add_co_u32_e32 v28, vcc, s48, v24
	v_lshl_or_b32 v243, v32, 13, v52
	s_nop 0
	v_addc_co_u32_e32 v29, vcc, 0, v25, vcc
	v_add_u32_e32 v40, 0x10000, v242
	v_add_u32_e32 v44, 0x80000, v243
	global_load_dwordx4 v[0:3], v[24:25], off
	s_nop 0
	global_load_dwordx4 v[4:7], v[4:5], off
	s_nop 0
	global_load_dwordx4 v[8:11], v[8:9], off
	s_nop 0
	global_load_dwordx4 v[12:15], v[12:13], off
	s_nop 0
	global_load_dwordx4 v[16:19], v[16:17], off
	s_nop 0
	global_load_dwordx4 v[20:23], v[20:21], off
	s_nop 0
	global_load_dwordx4 v[24:27], v[26:27], off
	s_nop 0
	global_load_dwordx4 v[28:31], v[28:29], off
	s_nop 0
	global_load_dwordx4 v[32:35], v242, s[4:5]
	global_load_dwordx4 v[36:39], v243, s[6:7]
	s_nop 0
	global_load_dwordx4 v[40:43], v40, s[4:5]
	s_nop 0
	global_load_dwordx4 v[44:47], v44, s[6:7]
	s_mulk_i32 s17, 0x2200
	s_lshl_b32 s52, s16, 2
	s_ashr_i32 s53, s50, 7
	s_add_i32 s48, s17, 0
	s_add_i32 s53, s53, s52
	s_add_i32 s48, s48, 0x12000
	v_cmp_gt_u32_e32 vcc, 8, v48
	v_mul_lo_u32 v50, v50, s96
	v_and_b32_e32 v48, 0x60, v51
	v_lshlrev_b32_e32 v51, 3, v128
	v_mul_u32_u24_e32 v49, 0x110, v49
	v_add3_u32 v49, s48, v168, v49
	s_waitcnt vmcnt(0)
	ds_write_b128 v49, v[0:3]
	s_waitcnt vmcnt(10)
	ds_write_b128 v49, v[4:7] offset:1088
	s_waitcnt vmcnt(9)
	ds_write_b128 v49, v[8:11] offset:2176
	s_waitcnt vmcnt(8)
	ds_write_b128 v49, v[12:15] offset:3264
	s_waitcnt vmcnt(7)
	ds_write_b128 v49, v[16:19] offset:4352
	s_waitcnt vmcnt(6)
	ds_write_b128 v49, v[20:23] offset:5440
	s_waitcnt vmcnt(5)
	ds_write_b128 v49, v[24:27] offset:6528
	s_waitcnt vmcnt(4)
	ds_write_b128 v49, v[28:31] offset:7616
	v_cndmask_b32_e64 v0, v248, 0, vcc
	v_add3_u32 v168, v52, v50, v0
	v_add_u32_e32 v0, 0, v168
	s_waitcnt vmcnt(3)
	ds_write_b128 v0, v[32:35]
	s_waitcnt vmcnt(1)
	ds_write_b128 v0, v[40:43] offset:4608
	v_mad_u64_u32 v[0:1], s[16:17], v53, s96, v[48:49]
	v_and_or_b32 v244, v51, 8, v0
	v_add_u32_e32 v0, 0, v244
	v_add_u32_e32 v1, 0x4800, v0
	v_add_u32_e32 v0, 0x6800, v0
	ds_write2_b64 v1, v[36:37], v[38:39] offset1:2
	s_waitcnt vmcnt(0)
	ds_write2_b64 v0, v[44:45], v[46:47] offset0:128 offset1:130
	s_waitcnt lgkmcnt(0)
	s_barrier
	s_add_i32 s51, s52, 4
	v_mov_b32_e32 v171, 0
	s_cmp_lt_i32 s53, 0
	v_mov_b32_e32 v170, v171
	v_mov_b32_e32 v47, v171
	v_mov_b32_e32 v46, v171
	v_mov_b32_e32 v45, v171
	v_mov_b32_e32 v44, v171
	v_mov_b32_e32 v43, v171
	v_mov_b32_e32 v42, v171
	v_mov_b32_e32 v41, v171
	v_mov_b32_e32 v40, v171
	v_mov_b32_e32 v39, v171
	v_mov_b32_e32 v38, v171
	v_mov_b32_e32 v37, v171
	v_mov_b32_e32 v36, v171
	v_mov_b32_e32 v35, v171
	v_mov_b32_e32 v34, v171
	v_mov_b32_e32 v33, v171
	v_mov_b32_e32 v32, v171
	v_mov_b32_e32 v111, v171
	v_mov_b32_e32 v110, v171
	v_mov_b32_e32 v109, v171
	v_mov_b32_e32 v108, v171
	v_mov_b32_e32 v107, v171
	v_mov_b32_e32 v106, v171
	v_mov_b32_e32 v105, v171
	v_mov_b32_e32 v104, v171
	v_mov_b32_e32 v103, v171
	v_mov_b32_e32 v102, v171
	v_mov_b32_e32 v101, v171
	v_mov_b32_e32 v100, v171
	v_mov_b32_e32 v99, v171
	v_mov_b32_e32 v98, v171
	v_mov_b32_e32 v97, v171
	v_mov_b32_e32 v96, v171
	v_mov_b32_e32 v15, v171
	v_mov_b32_e32 v14, v171
	v_mov_b32_e32 v13, v171
	v_mov_b32_e32 v12, v171
	v_mov_b32_e32 v11, v171
	v_mov_b32_e32 v10, v171
	v_mov_b32_e32 v9, v171
	v_mov_b32_e32 v8, v171
	v_mov_b32_e32 v7, v171
	v_mov_b32_e32 v6, v171
	v_mov_b32_e32 v5, v171
	v_mov_b32_e32 v4, v171
	v_mov_b32_e32 v3, v171
	v_mov_b32_e32 v2, v171
	v_mov_b32_e32 v1, v171
	v_mov_b32_e32 v0, v171
	v_mov_b32_e32 v79, v171
	v_mov_b32_e32 v78, v171
	v_mov_b32_e32 v77, v171
	v_mov_b32_e32 v76, v171
	v_mov_b32_e32 v75, v171
	v_mov_b32_e32 v74, v171
	v_mov_b32_e32 v73, v171
	v_mov_b32_e32 v72, v171
	v_mov_b32_e32 v71, v171
	v_mov_b32_e32 v70, v171
	v_mov_b32_e32 v69, v171
	v_mov_b32_e32 v68, v171
	v_mov_b32_e32 v67, v171
	v_mov_b32_e32 v66, v171
	v_mov_b32_e32 v65, v171
	v_mov_b32_e32 v64, v171
	v_mov_b32_e32 v127, v171
	v_mov_b32_e32 v126, v171
	v_mov_b32_e32 v125, v171
	v_mov_b32_e32 v124, v171
	v_mov_b32_e32 v123, v171
	v_mov_b32_e32 v122, v171
	v_mov_b32_e32 v121, v171
	v_mov_b32_e32 v120, v171
	v_mov_b32_e32 v119, v171
	v_mov_b32_e32 v118, v171
	v_mov_b32_e32 v117, v171
	v_mov_b32_e32 v116, v171
	v_mov_b32_e32 v115, v171
	v_mov_b32_e32 v114, v171
	v_mov_b32_e32 v113, v171
	v_mov_b32_e32 v112, v171
	v_mov_b32_e32 v95, v171
	v_mov_b32_e32 v94, v171
	v_mov_b32_e32 v93, v171
	v_mov_b32_e32 v92, v171
	v_mov_b32_e32 v91, v171
	v_mov_b32_e32 v90, v171
	v_mov_b32_e32 v89, v171
	v_mov_b32_e32 v88, v171
	v_mov_b32_e32 v87, v171
	v_mov_b32_e32 v86, v171
	v_mov_b32_e32 v85, v171
	v_mov_b32_e32 v84, v171
	v_mov_b32_e32 v83, v171
	v_mov_b32_e32 v82, v171
	v_mov_b32_e32 v81, v171
	v_mov_b32_e32 v80, v171
	v_mov_b32_e32 v63, v171
	v_mov_b32_e32 v62, v171
	v_mov_b32_e32 v61, v171
	v_mov_b32_e32 v60, v171
	v_mov_b32_e32 v59, v171
	v_mov_b32_e32 v58, v171
	v_mov_b32_e32 v57, v171
	v_mov_b32_e32 v56, v171
	v_mov_b32_e32 v55, v171
	v_mov_b32_e32 v54, v171
	v_mov_b32_e32 v53, v171
	v_mov_b32_e32 v52, v171
	v_mov_b32_e32 v51, v171
	v_mov_b32_e32 v50, v171
	v_mov_b32_e32 v49, v171
	v_mov_b32_e32 v48, v171
	v_mov_b32_e32 v31, v171
	v_mov_b32_e32 v30, v171
	v_mov_b32_e32 v29, v171
	v_mov_b32_e32 v28, v171
	v_mov_b32_e32 v27, v171
	v_mov_b32_e32 v26, v171
	v_mov_b32_e32 v25, v171
	v_mov_b32_e32 v24, v171
	v_mov_b32_e32 v23, v171
	v_mov_b32_e32 v22, v171
	v_mov_b32_e32 v21, v171
	v_mov_b32_e32 v20, v171
	v_mov_b32_e32 v19, v171
	v_mov_b32_e32 v18, v171
	v_mov_b32_e32 v17, v171
	v_mov_b32_e32 v16, v171
	s_cbranch_scc1 .LBB0_292
	v_and_b32_e32 v0, 31, v128
	v_lshrrev_b32_e32 v1, 1, v128
	v_mov_b32_e32 v2, s48
	s_movk_i32 s16, 0x110
	v_and_b32_e32 v1, 16, v1
	v_mad_u32_u24 v2, v0, s16, v2
	v_mul_u32_u24_e32 v0, 0x90, v0
	v_mov_b32_e32 v16, 0
	s_or_b32 s16, s52, 3
	v_add3_u32 v245, 0, v0, v1
	s_add_i32 s17, s53, 1
	s_mov_b32 s55, 0
	v_add_u32_e32 v246, v2, v1
	v_mov_b32_e32 v17, v16
	v_mov_b32_e32 v18, v16
	v_mov_b32_e32 v19, v16
	v_mov_b32_e32 v20, v16
	v_mov_b32_e32 v21, v16
	v_mov_b32_e32 v22, v16
	v_mov_b32_e32 v23, v16
	v_mov_b32_e32 v24, v16
	v_mov_b32_e32 v25, v16
	v_mov_b32_e32 v26, v16
	v_mov_b32_e32 v27, v16
	v_mov_b32_e32 v28, v16
	v_mov_b32_e32 v29, v16
	v_mov_b32_e32 v30, v16
	v_mov_b32_e32 v31, v16
	v_mov_b32_e32 v48, v16
	v_mov_b32_e32 v49, v16
	v_mov_b32_e32 v50, v16
	v_mov_b32_e32 v51, v16
	v_mov_b32_e32 v52, v16
	v_mov_b32_e32 v53, v16
	v_mov_b32_e32 v54, v16
	v_mov_b32_e32 v55, v16
	v_mov_b32_e32 v56, v16
	v_mov_b32_e32 v57, v16
	v_mov_b32_e32 v58, v16
	v_mov_b32_e32 v59, v16
	v_mov_b32_e32 v60, v16
	v_mov_b32_e32 v61, v16
	v_mov_b32_e32 v62, v16
	v_mov_b32_e32 v63, v16
	v_mov_b32_e32 v80, v16
	v_mov_b32_e32 v81, v16
	v_mov_b32_e32 v82, v16
	v_mov_b32_e32 v83, v16
	v_mov_b32_e32 v84, v16
	v_mov_b32_e32 v85, v16
	v_mov_b32_e32 v86, v16
	v_mov_b32_e32 v87, v16
	v_mov_b32_e32 v88, v16
	v_mov_b32_e32 v89, v16
	v_mov_b32_e32 v90, v16
	v_mov_b32_e32 v91, v16
	v_mov_b32_e32 v92, v16
	v_mov_b32_e32 v93, v16
	v_mov_b32_e32 v94, v16
	v_mov_b32_e32 v95, v16
	v_mov_b32_e32 v0, v16
	v_mov_b32_e32 v1, v16
	v_mov_b32_e32 v2, v16
	v_mov_b32_e32 v3, v16
	v_mov_b32_e32 v4, v16
	v_mov_b32_e32 v5, v16
	v_mov_b32_e32 v6, v16
	v_mov_b32_e32 v7, v16
	v_mov_b32_e32 v8, v16
	v_mov_b32_e32 v9, v16
	v_mov_b32_e32 v10, v16
	v_mov_b32_e32 v11, v16
	v_mov_b32_e32 v12, v16
	v_mov_b32_e32 v13, v16
	v_mov_b32_e32 v14, v16
	v_mov_b32_e32 v15, v16
	v_mov_b32_e32 v64, v16
	v_mov_b32_e32 v65, v16
	v_mov_b32_e32 v66, v16
	v_mov_b32_e32 v67, v16
	v_mov_b32_e32 v68, v16
	v_mov_b32_e32 v69, v16
	v_mov_b32_e32 v70, v16
	v_mov_b32_e32 v71, v16
	v_mov_b32_e32 v72, v16
	v_mov_b32_e32 v73, v16
	v_mov_b32_e32 v74, v16
	v_mov_b32_e32 v75, v16
	v_mov_b32_e32 v76, v16
	v_mov_b32_e32 v77, v16
	v_mov_b32_e32 v78, v16
	v_mov_b32_e32 v79, v16
	v_mov_b32_e32 v112, v16
	v_mov_b32_e32 v113, v16
	v_mov_b32_e32 v114, v16
	v_mov_b32_e32 v115, v16
	v_mov_b32_e32 v116, v16
	v_mov_b32_e32 v117, v16
	v_mov_b32_e32 v118, v16
	v_mov_b32_e32 v119, v16
	v_mov_b32_e32 v120, v16
	v_mov_b32_e32 v121, v16
	v_mov_b32_e32 v122, v16
	v_mov_b32_e32 v123, v16
	v_mov_b32_e32 v124, v16
	v_mov_b32_e32 v125, v16
	v_mov_b32_e32 v126, v16
	v_mov_b32_e32 v127, v16
	v_mov_b32_e32 v32, v16
	v_mov_b32_e32 v33, v16
	v_mov_b32_e32 v34, v16
	v_mov_b32_e32 v35, v16
	v_mov_b32_e32 v36, v16
	v_mov_b32_e32 v37, v16
	v_mov_b32_e32 v38, v16
	v_mov_b32_e32 v39, v16
	v_mov_b32_e32 v40, v16
	v_mov_b32_e32 v41, v16
	v_mov_b32_e32 v42, v16
	v_mov_b32_e32 v43, v16
	v_mov_b32_e32 v44, v16
	v_mov_b32_e32 v45, v16
	v_mov_b32_e32 v46, v16
	v_mov_b32_e32 v47, v16
	v_mov_b32_e32 v96, v16
	v_mov_b32_e32 v97, v16
	v_mov_b32_e32 v98, v16
	v_mov_b32_e32 v99, v16
	v_mov_b32_e32 v100, v16
	v_mov_b32_e32 v101, v16
	v_mov_b32_e32 v102, v16
	v_mov_b32_e32 v103, v16
	v_mov_b32_e32 v104, v16
	v_mov_b32_e32 v105, v16
	v_mov_b32_e32 v106, v16
	v_mov_b32_e32 v107, v16
	v_mov_b32_e32 v108, v16
	v_mov_b32_e32 v109, v16
	v_mov_b32_e32 v110, v16
	v_mov_b32_e32 v111, v16
	v_mov_b32_e32 v170, v16
	v_mov_b32_e32 v171, v16
	s_cmpk_lt_u32 s81, 0x100
	s_cbranch_scc1 .Lattn_noprio
	s_setprio 1
.Lattn_noprio:
.LBB0_290:
	s_add_i32 s54, s55, 1
	s_cmp_lt_u32 s54, s51
	s_cselect_b32 s56, s54, s16
	v_lshl_add_u32 v128, s56, 17, v242
	v_lshl_add_u32 v129, s56, 7, v243
	v_add_u32_e32 v130, 0x10000, v128
	global_load_dwordx4 v[152:155], v128, s[4:5]
	global_load_dwordx4 v[148:151], v129, s[6:7]
	v_add_u32_e32 v128, 0x80000, v129
	global_load_dwordx4 v[156:159], v130, s[4:5]
	global_load_dwordx4 v[144:147], v128, s[6:7]
	s_bitcmp1_b32 s55, 0
	s_cselect_b32 s55, 0x9000, 0
	v_add_u32_e32 v247, s55, v245
	ds_read_b128 v[128:131], v247
	ds_read_b128 v[160:163], v247 offset:32
	ds_read_b128 v[132:135], v246
	ds_read_b128 v[164:167], v246 offset:32
	ds_read_b128 v[172:175], v247 offset:64
	ds_read_b128 v[176:179], v246 offset:64
	s_waitcnt lgkmcnt(3)
	v_mfma_f32_32x32x16_bf16 v[128:143], v[128:131], v[132:135], 0
	s_waitcnt lgkmcnt(2)
	v_mfma_f32_32x32x16_bf16 v[128:143], v[160:163], v[164:167], v[128:143]
	ds_read_b128 v[160:163], v247 offset:96
	ds_read_b128 v[164:167], v246 offset:96
	s_waitcnt lgkmcnt(2)
	v_mfma_f32_32x32x16_bf16 v[128:143], v[172:175], v[176:179], v[128:143]
	s_waitcnt lgkmcnt(0)
	v_mfma_f32_32x32x16_bf16 v[128:143], v[160:163], v[164:167], v[128:143]
	s_nop 11
	v_exp_f32_e32 v164, v128
	v_exp_f32_e32 v226, v129
	v_exp_f32_e32 v160, v130
	v_exp_f32_e32 v224, v131
	v_exp_f32_e32 v166, v132
	v_exp_f32_e32 v222, v133
	v_exp_f32_e32 v162, v134
	v_exp_f32_e32 v220, v135
	v_exp_f32_e32 v218, v136
	v_exp_f32_e32 v214, v137
	v_exp_f32_e32 v212, v138
	v_exp_f32_e32 v210, v139
	v_exp_f32_e32 v178, v140
	v_exp_f32_e32 v176, v141
	v_exp_f32_e32 v174, v142
	v_exp_f32_e32 v172, v143
	v_cvt_pk_bf16_f32 v248, v164, v226
	v_cvt_pk_bf16_f32 v234, v218, v214
	v_cvt_pk_bf16_f32 v249, v160, v224
	v_cvt_pk_bf16_f32 v235, v212, v210
	v_cvt_pk_bf16_f32 v250, v166, v222
	v_cvt_pk_bf16_f32 v236, v178, v176
	v_cvt_pk_bf16_f32 v251, v162, v220
	v_cvt_pk_bf16_f32 v237, v174, v172
	ds_read_b128 v[128:131], v247 offset:4608
	ds_read_b128 v[180:183], v247 offset:4640
	ds_read_b128 v[132:135], v246
	ds_read_b128 v[184:187], v246 offset:32
	ds_read_b128 v[188:191], v247 offset:4672
	ds_read_b128 v[192:195], v246 offset:64
	s_waitcnt lgkmcnt(3)
	v_mfma_f32_32x32x16_bf16 v[128:143], v[128:131], v[132:135], 0
	s_waitcnt lgkmcnt(2)
	v_mfma_f32_32x32x16_bf16 v[128:143], v[180:183], v[184:187], v[128:143]
	ds_read_b128 v[180:183], v247 offset:4704
	ds_read_b128 v[184:187], v246 offset:96
	s_waitcnt lgkmcnt(2)
	v_mfma_f32_32x32x16_bf16 v[128:143], v[188:191], v[192:195], v[128:143]
	s_waitcnt lgkmcnt(0)
	v_mfma_f32_32x32x16_bf16 v[128:143], v[180:183], v[184:187], v[128:143]
	s_nop 11
	v_exp_f32_e32 v216, v128
	v_exp_f32_e32 v208, v129
	v_exp_f32_e32 v206, v130
	v_exp_f32_e32 v204, v131
	v_exp_f32_e32 v202, v132
	v_exp_f32_e32 v200, v133
	v_exp_f32_e32 v198, v134
	v_exp_f32_e32 v196, v135
	v_exp_f32_e32 v194, v136
	v_exp_f32_e32 v192, v137
	v_exp_f32_e32 v190, v138
	v_exp_f32_e32 v188, v139
	v_exp_f32_e32 v186, v140
	v_exp_f32_e32 v184, v141
	v_exp_f32_e32 v182, v142
	v_exp_f32_e32 v180, v143
	v_cvt_pk_bf16_f32 v128, v216, v208
	v_cvt_pk_bf16_f32 v132, v194, v192
	v_cvt_pk_bf16_f32 v129, v206, v204
	v_cvt_pk_bf16_f32 v133, v190, v188
	v_cvt_pk_bf16_f32 v130, v202, v200
	v_cvt_pk_bf16_f32 v134, v186, v184
	v_cvt_pk_bf16_f32 v131, v198, v196
	v_cvt_pk_bf16_f32 v135, v182, v180
	ds_read_b128 v[136:139], v247 offset:18432
	ds_read_b128 v[140:143], v247 offset:18464
	ds_read_b128 v[228:231], v247 offset:18496
	ds_read_b128 v[238:241], v247 offset:18528
	s_waitcnt lgkmcnt(3)
	v_mfma_f32_32x32x16_bf16 v[32:47], v[248:251], v[136:139], v[32:47]
	ds_read_b128 v[136:139], v247 offset:23040
	s_waitcnt lgkmcnt(3)
	v_mfma_f32_32x32x16_bf16 v[32:47], v[234:237], v[140:143], v[32:47]
	ds_read_b128 v[140:143], v247 offset:23072
	s_waitcnt lgkmcnt(3)
	v_mfma_f32_32x32x16_bf16 v[32:47], v[128:131], v[228:231], v[32:47]
	ds_read_b128 v[228:231], v247 offset:23104
	s_waitcnt lgkmcnt(3)
	v_mfma_f32_32x32x16_bf16 v[32:47], v[132:135], v[238:241], v[32:47]
	ds_read_b128 v[238:241], v247 offset:23136
	s_waitcnt lgkmcnt(3)
	v_mfma_f32_32x32x16_bf16 v[112:127], v[248:251], v[136:139], v[112:127]
	ds_read_b128 v[136:139], v247 offset:27648
	s_waitcnt lgkmcnt(3)
	v_mfma_f32_32x32x16_bf16 v[112:127], v[234:237], v[140:143], v[112:127]
	ds_read_b128 v[140:143], v247 offset:27680
	s_waitcnt lgkmcnt(3)
	v_mfma_f32_32x32x16_bf16 v[112:127], v[128:131], v[228:231], v[112:127]
	ds_read_b128 v[228:231], v247 offset:27712
	s_waitcnt lgkmcnt(3)
	v_mfma_f32_32x32x16_bf16 v[112:127], v[132:135], v[238:241], v[112:127]
	ds_read_b128 v[238:241], v247 offset:27744
	s_waitcnt lgkmcnt(3)
	v_mfma_f32_32x32x16_bf16 v[64:79], v[248:251], v[136:139], v[64:79]
	ds_read_b128 v[136:139], v247 offset:32256
	s_waitcnt lgkmcnt(3)
	v_mfma_f32_32x32x16_bf16 v[64:79], v[234:237], v[140:143], v[64:79]
	ds_read_b128 v[140:143], v247 offset:32288
	s_waitcnt lgkmcnt(3)
	v_mfma_f32_32x32x16_bf16 v[64:79], v[128:131], v[228:231], v[64:79]
	ds_read_b128 v[228:231], v247 offset:32320
	s_waitcnt lgkmcnt(3)
	v_mfma_f32_32x32x16_bf16 v[64:79], v[132:135], v[238:241], v[64:79]
	ds_read_b128 v[238:241], v247 offset:32352
	s_waitcnt lgkmcnt(3)
	v_mfma_f32_32x32x16_bf16 v[0:15], v[248:251], v[136:139], v[0:15]
	s_waitcnt lgkmcnt(2)
	v_mfma_f32_32x32x16_bf16 v[0:15], v[234:237], v[140:143], v[0:15]
	s_waitcnt lgkmcnt(1)
	v_mfma_f32_32x32x16_bf16 v[0:15], v[128:131], v[228:231], v[0:15]
	s_waitcnt lgkmcnt(0)
	v_mfma_f32_32x32x16_bf16 v[0:15], v[132:135], v[238:241], v[0:15]
	ds_read_b128 v[128:131], v247 offset:9216
	ds_read_b128 v[228:231], v247 offset:9248
	ds_read_b128 v[132:135], v246 offset:128
	ds_read_b128 v[234:237], v246 offset:160
	ds_read_b128 v[238:241], v247 offset:9280
	ds_read_b128 v[248:251], v246 offset:192
	s_waitcnt lgkmcnt(3)
	v_mfma_f32_32x32x16_bf16 v[128:143], v[128:131], v[132:135], 0
	s_waitcnt lgkmcnt(2)
	v_mfma_f32_32x32x16_bf16 v[128:143], v[228:231], v[234:237], v[128:143]
	ds_read_b128 v[228:231], v247 offset:9312
	ds_read_b128 v[234:237], v246 offset:224
	s_waitcnt lgkmcnt(2)
	v_mfma_f32_32x32x16_bf16 v[128:143], v[238:241], v[248:251], v[128:143]
	s_waitcnt lgkmcnt(0)
	v_mfma_f32_32x32x16_bf16 v[128:143], v[228:231], v[234:237], v[128:143]
	s_nop 11
	v_exp_f32_e32 v165, v128
	v_exp_f32_e32 v227, v129
	v_exp_f32_e32 v161, v130
	v_exp_f32_e32 v225, v131
	v_exp_f32_e32 v167, v132
	v_pk_add_f32 v[128:129], v[164:165], 0 op_sel_hi:[1,0]
	v_exp_f32_e32 v223, v133
	v_pk_add_f32 v[128:129], v[226:227], v[128:129]
	v_exp_f32_e32 v163, v134
	v_pk_add_f32 v[128:129], v[160:161], v[128:129]
	v_exp_f32_e32 v221, v135
	v_pk_add_f32 v[128:129], v[224:225], v[128:129]
	v_exp_f32_e32 v219, v136
	v_pk_add_f32 v[128:129], v[166:167], v[128:129]
	v_exp_f32_e32 v215, v137
	v_pk_add_f32 v[128:129], v[222:223], v[128:129]
	v_exp_f32_e32 v213, v138
	v_pk_add_f32 v[230:231], v[162:163], v[128:129]
	v_exp_f32_e32 v211, v139
	v_exp_f32_e32 v179, v140
	v_exp_f32_e32 v177, v141
	v_exp_f32_e32 v175, v142
	v_exp_f32_e32 v173, v143
	v_cvt_pk_bf16_f32 v164, v165, v227
	v_cvt_pk_bf16_f32 v160, v219, v215
	v_cvt_pk_bf16_f32 v165, v161, v225
	v_cvt_pk_bf16_f32 v161, v213, v211
	v_cvt_pk_bf16_f32 v166, v167, v223
	v_cvt_pk_bf16_f32 v162, v179, v177
	v_cvt_pk_bf16_f32 v167, v163, v221
	v_cvt_pk_bf16_f32 v163, v175, v173
	ds_read_b128 v[128:131], v247 offset:13824
	ds_read_b128 v[222:225], v247 offset:13856
	ds_read_b128 v[132:135], v246 offset:128
	ds_read_b128 v[226:229], v246 offset:160
	ds_read_b128 v[234:237], v247 offset:13888
	ds_read_b128 v[238:241], v246 offset:192
	s_waitcnt lgkmcnt(3)
	v_mfma_f32_32x32x16_bf16 v[128:143], v[128:131], v[132:135], 0
	s_waitcnt lgkmcnt(2)
	v_mfma_f32_32x32x16_bf16 v[128:143], v[222:225], v[226:229], v[128:143]
	ds_read_b128 v[222:225], v247 offset:13920
	ds_read_b128 v[226:229], v246 offset:224
	s_waitcnt lgkmcnt(2)
	v_mfma_f32_32x32x16_bf16 v[128:143], v[234:237], v[238:241], v[128:143]
	s_waitcnt lgkmcnt(0)
	v_mfma_f32_32x32x16_bf16 v[128:143], v[222:225], v[226:229], v[128:143]
	s_nop 11
	v_exp_f32_e32 v217, v128
	v_exp_f32_e32 v209, v129
	v_exp_f32_e32 v207, v130
	v_exp_f32_e32 v205, v131
	v_exp_f32_e32 v203, v132
	v_exp_f32_e32 v195, v136
	v_exp_f32_e32 v193, v137
	v_pk_add_f32 v[136:137], v[216:217], 0 op_sel_hi:[1,0]
	v_exp_f32_e32 v201, v133
	v_pk_add_f32 v[136:137], v[208:209], v[136:137]
	v_exp_f32_e32 v199, v134
	v_pk_add_f32 v[136:137], v[206:207], v[136:137]
	v_exp_f32_e32 v197, v135
	v_pk_add_f32 v[136:137], v[204:205], v[136:137]
	v_exp_f32_e32 v191, v138
	v_pk_add_f32 v[136:137], v[202:203], v[136:137]
	v_pk_add_f32 v[128:129], v[220:221], v[230:231]
	v_pk_add_f32 v[136:137], v[200:201], v[136:137]
	v_exp_f32_e32 v189, v139
	v_pk_add_f32 v[136:137], v[198:199], v[136:137]
	v_pk_add_f32 v[128:129], v[218:219], v[128:129]
	v_pk_add_f32 v[136:137], v[196:197], v[136:137]
	v_exp_f32_e32 v187, v140
	v_pk_add_f32 v[128:129], v[214:215], v[128:129]
	v_pk_add_f32 v[136:137], v[194:195], v[136:137]
	v_exp_f32_e32 v185, v141
	v_pk_add_f32 v[128:129], v[212:213], v[128:129]
	v_pk_add_f32 v[136:137], v[192:193], v[136:137]
	v_exp_f32_e32 v183, v142
	v_pk_add_f32 v[138:139], v[210:211], v[128:129]
	v_pk_add_f32 v[136:137], v[190:191], v[136:137]
	v_exp_f32_e32 v181, v143
	v_pk_add_f32 v[138:139], v[178:179], v[138:139]
	v_pk_add_f32 v[136:137], v[188:189], v[136:137]
	v_pk_add_f32 v[138:139], v[176:177], v[138:139]
	v_pk_add_f32 v[136:137], v[186:187], v[136:137]
	v_pk_add_f32 v[138:139], v[174:175], v[138:139]
	v_pk_add_f32 v[136:137], v[184:185], v[136:137]
	v_pk_add_f32 v[138:139], v[172:173], v[138:139]
	v_pk_add_f32 v[136:137], v[182:183], v[136:137]
	v_pk_add_f32 v[138:139], v[170:171], v[138:139]
	v_pk_add_f32 v[136:137], v[180:181], v[136:137]
	v_cvt_pk_bf16_f32 v128, v217, v209
	v_cvt_pk_bf16_f32 v132, v195, v193
	v_cvt_pk_bf16_f32 v129, v207, v205
	v_cvt_pk_bf16_f32 v133, v191, v189
	v_cvt_pk_bf16_f32 v130, v203, v201
	s_nop 0
	v_pk_add_f32 v[170:171], v[138:139], v[136:137]
	v_cvt_pk_bf16_f32 v134, v187, v185
	v_cvt_pk_bf16_f32 v131, v199, v197
	v_cvt_pk_bf16_f32 v135, v183, v181
	ds_read_b128 v[136:139], v247 offset:18432
	ds_read_b128 v[140:143], v247 offset:18464
	ds_read_b128 v[172:175], v247 offset:18496
	ds_read_b128 v[176:179], v247 offset:18528
	s_waitcnt lgkmcnt(3)
	v_mfma_f32_32x32x16_bf16 v[96:111], v[164:167], v[136:139], v[96:111]
	ds_read_b128 v[136:139], v247 offset:23040
	s_waitcnt lgkmcnt(3)
	v_mfma_f32_32x32x16_bf16 v[96:111], v[160:163], v[140:143], v[96:111]
	ds_read_b128 v[140:143], v247 offset:23072
	s_waitcnt lgkmcnt(3)
	v_mfma_f32_32x32x16_bf16 v[96:111], v[128:131], v[172:175], v[96:111]
	ds_read_b128 v[172:175], v247 offset:23104
	s_waitcnt lgkmcnt(3)
	v_mfma_f32_32x32x16_bf16 v[96:111], v[132:135], v[176:179], v[96:111]
	ds_read_b128 v[176:179], v247 offset:23136
	s_waitcnt lgkmcnt(3)
	v_mfma_f32_32x32x16_bf16 v[80:95], v[164:167], v[136:139], v[80:95]
	ds_read_b128 v[136:139], v247 offset:27648
	s_waitcnt lgkmcnt(3)
	v_mfma_f32_32x32x16_bf16 v[80:95], v[160:163], v[140:143], v[80:95]
	ds_read_b128 v[140:143], v247 offset:27680
	s_waitcnt lgkmcnt(3)
	v_mfma_f32_32x32x16_bf16 v[80:95], v[128:131], v[172:175], v[80:95]
	ds_read_b128 v[172:175], v247 offset:27712
	s_waitcnt lgkmcnt(3)
	v_mfma_f32_32x32x16_bf16 v[80:95], v[132:135], v[176:179], v[80:95]
	ds_read_b128 v[176:179], v247 offset:27744
	s_waitcnt lgkmcnt(3)
	v_mfma_f32_32x32x16_bf16 v[48:63], v[164:167], v[136:139], v[48:63]
	ds_read_b128 v[136:139], v247 offset:32256
	s_waitcnt lgkmcnt(3)
	v_mfma_f32_32x32x16_bf16 v[48:63], v[160:163], v[140:143], v[48:63]
	ds_read_b128 v[140:143], v247 offset:32288
	s_waitcnt lgkmcnt(3)
	v_mfma_f32_32x32x16_bf16 v[48:63], v[128:131], v[172:175], v[48:63]
	ds_read_b128 v[172:175], v247 offset:32320
	s_waitcnt lgkmcnt(3)
	v_mfma_f32_32x32x16_bf16 v[48:63], v[132:135], v[176:179], v[48:63]
	ds_read_b128 v[176:179], v247 offset:32352
	s_waitcnt lgkmcnt(3)
	v_mfma_f32_32x32x16_bf16 v[16:31], v[164:167], v[136:139], v[16:31]
	s_waitcnt lgkmcnt(2)
	v_mfma_f32_32x32x16_bf16 v[16:31], v[160:163], v[140:143], v[16:31]
	s_waitcnt lgkmcnt(1)
	v_mfma_f32_32x32x16_bf16 v[16:31], v[128:131], v[172:175], v[16:31]
	s_waitcnt lgkmcnt(0)
	v_mfma_f32_32x32x16_bf16 v[16:31], v[132:135], v[176:179], v[16:31]
	s_bitcmp1_b32 s54, 0
	s_cselect_b32 s55, 0x9000, 0
	s_add_i32 s55, s55, 0
	v_add_u32_e32 v128, s55, v168
	s_waitcnt vmcnt(3)
	ds_write_b128 v128, v[152:155]
	s_waitcnt vmcnt(1)
	ds_write_b128 v128, v[156:159] offset:4608
	v_add_u32_e32 v128, s55, v244
	v_add_u32_e32 v129, 0x4800, v128
	v_add_u32_e32 v128, 0x6800, v128
	ds_write2_b64 v129, v[148:149], v[150:151] offset1:2
	s_waitcnt vmcnt(0)
	ds_write2_b64 v128, v[144:145], v[146:147] offset0:128 offset1:130
	s_waitcnt lgkmcnt(0)
	s_barrier
	s_cmp_eq_u32 s17, s54
	s_mov_b32 s55, s54
	s_cbranch_scc0 .LBB0_290
	s_setprio 0
	v_mov_b32_e32 v238, 0x3727c5ac
	v_mov_b32_e32 v248, 0x2400
